# phase-0 weight transposes remapped: dwordx4 loads, full 128B-line bf16 stores via bpermute'd row pointers (5 sites)
# speedup vs baseline: 1.0624x; 1.0287x over previous
.LBB0_42:
	s_andn2_b64 vcc, exec, s[4:5]
	s_cbranch_vccnz .LBB0_45
	s_load_dwordx2 s[44:45], s[8:9], 0x90
	s_load_dwordx2 s[78:79], s[8:9], 0xa8
	s_lshr_b32 s4, s19, 6
	s_mov_b32 s5, s13
	s_lshl_b64 s[6:7], s[4:5], 20
	s_or_b64 s[6:7], s[6:7], s[12:13]
	s_lshl_b64 s[4:5], s[4:5], 21
	s_lshl_b32 s80, s17, 6
	s_waitcnt lgkmcnt(0)
	s_add_u32 s6, s44, s6
	s_addc_u32 s7, s45, s7
	v_lshl_add_u64 v[0:1], s[6:7], 0, v[128:129]
	s_add_u32 s6, s78, s43
	s_addc_u32 s7, s79, 0
	v_bitop3_b32 v2, s80, v157, v130 bitop3:0xc8
	s_add_u32 s4, s6, s4
	v_add_lshl_u32 v2, v153, v2, 11
	v_mov_b32_e32 v3, v129
	s_addc_u32 s5, s7, s5
	v_lshl_add_u64 v[2:3], s[4:5], 0, v[2:3]
	v_lshl_add_u64 v[2:3], v[2:3], 0, s[26:27]
	s_mov_b64 s[6:7], 0
	v_lshl_add_u64 v[8:9], v[0:1], 0, s[6:7]
	v_and_b32_e32 v10, 7, v130
	v_lshrrev_b32_e32 v11, 3, v130
	v_readfirstlane_b32 s4, v8
	v_readfirstlane_b32 s5, v9
	v_lshlrev_b32_e32 v10, 15, v10
	v_lshl_add_u32 v10, v11, 4, v10
	v_lshlrev_b32_e32 v12, 4, v11
	v_mov_b32_e32 v11, 0
	v_lshl_add_u64 v[8:9], s[4:5], 0, v[10:11]
	global_load_dwordx4 v[16:19], v[8:9], off nt
	s_mov_b64 s[4:5], 0x1000
	v_lshl_add_u64 v[102:103], v[8:9], 0, s[4:5]
	global_load_dwordx4 v[20:23], v[102:103], off nt
	s_mov_b64 s[4:5], 0x2000
	v_lshl_add_u64 v[104:105], v[8:9], 0, s[4:5]
	global_load_dwordx4 v[24:27], v[104:105], off nt
	s_mov_b64 s[4:5], 0x3000
	v_lshl_add_u64 v[106:107], v[8:9], 0, s[4:5]
	global_load_dwordx4 v[28:31], v[106:107], off nt
	s_mov_b64 s[4:5], 0x4000
	v_lshl_add_u64 v[108:109], v[8:9], 0, s[4:5]
	global_load_dwordx4 v[32:35], v[108:109], off nt
	s_mov_b64 s[4:5], 0x5000
	v_lshl_add_u64 v[110:111], v[8:9], 0, s[4:5]
	global_load_dwordx4 v[36:39], v[110:111], off nt
	s_mov_b64 s[4:5], 0x6000
	v_lshl_add_u64 v[112:113], v[8:9], 0, s[4:5]
	global_load_dwordx4 v[40:43], v[112:113], off nt
	s_mov_b64 s[4:5], 0x7000
	v_lshl_add_u64 v[114:115], v[8:9], 0, s[4:5]
	global_load_dwordx4 v[44:47], v[114:115], off nt
	global_load_dwordx4 v[48:51], v[8:9], off offset:128 nt
	global_load_dwordx4 v[52:55], v[102:103], off offset:128 nt
	global_load_dwordx4 v[56:59], v[104:105], off offset:128 nt
	global_load_dwordx4 v[60:63], v[106:107], off offset:128 nt
	global_load_dwordx4 v[64:67], v[108:109], off offset:128 nt
	global_load_dwordx4 v[68:71], v[110:111], off offset:128 nt
	global_load_dwordx4 v[72:75], v[112:113], off offset:128 nt
	global_load_dwordx4 v[76:79], v[114:115], off offset:128 nt
	ds_bpermute_b32 v80, v12, v2
	ds_bpermute_b32 v81, v12, v3
	v_add_u32_e32 v13, 4, v12
	ds_bpermute_b32 v82, v13, v2
	ds_bpermute_b32 v83, v13, v3
	v_add_u32_e32 v13, 8, v12
	ds_bpermute_b32 v84, v13, v2
	ds_bpermute_b32 v85, v13, v3
	v_add_u32_e32 v13, 12, v12
	ds_bpermute_b32 v86, v13, v2
	ds_bpermute_b32 v87, v13, v3
	v_add_u32_e32 v13, 128, v12
	ds_bpermute_b32 v88, v13, v2
	ds_bpermute_b32 v89, v13, v3
	v_add_u32_e32 v13, 132, v12
	ds_bpermute_b32 v90, v13, v2
	ds_bpermute_b32 v91, v13, v3
	v_add_u32_e32 v13, 136, v12
	ds_bpermute_b32 v92, v13, v2
	ds_bpermute_b32 v93, v13, v3
	v_add_u32_e32 v13, 140, v12
	ds_bpermute_b32 v94, v13, v2
	ds_bpermute_b32 v95, v13, v3
	v_and_b32_e32 v14, 7, v130
	v_lshlrev_b32_e32 v14, 4, v14
	v_mov_b32_e32 v15, 0
	s_waitcnt lgkmcnt(0)
	v_lshl_add_u64 v[80:81], v[80:81], 0, v[14:15]
	v_lshl_add_u64 v[82:83], v[82:83], 0, v[14:15]
	v_lshl_add_u64 v[84:85], v[84:85], 0, v[14:15]
	v_lshl_add_u64 v[86:87], v[86:87], 0, v[14:15]
	v_lshl_add_u64 v[88:89], v[88:89], 0, v[14:15]
	v_lshl_add_u64 v[90:91], v[90:91], 0, v[14:15]
	v_lshl_add_u64 v[92:93], v[92:93], 0, v[14:15]
	v_lshl_add_u64 v[94:95], v[94:95], 0, v[14:15]
	s_waitcnt vmcnt(8)
	v_cvt_pk_bf16_f32 v116, v16, v20
	v_cvt_pk_bf16_f32 v117, v24, v28
	v_cvt_pk_bf16_f32 v118, v32, v36
	v_cvt_pk_bf16_f32 v119, v40, v44
	global_store_dwordx4 v[80:81], v[116:119], off offset:-32
	v_cvt_pk_bf16_f32 v120, v17, v21
	v_cvt_pk_bf16_f32 v121, v25, v29
	v_cvt_pk_bf16_f32 v122, v33, v37
	v_cvt_pk_bf16_f32 v123, v41, v45
	global_store_dwordx4 v[82:83], v[120:123], off offset:-32
	v_cvt_pk_bf16_f32 v124, v18, v22
	v_cvt_pk_bf16_f32 v125, v26, v30
	v_cvt_pk_bf16_f32 v126, v34, v38
	v_cvt_pk_bf16_f32 v127, v42, v46
	global_store_dwordx4 v[84:85], v[124:127], off offset:-32
	v_cvt_pk_bf16_f32 v116, v19, v23
	v_cvt_pk_bf16_f32 v117, v27, v31
	v_cvt_pk_bf16_f32 v118, v35, v39
	v_cvt_pk_bf16_f32 v119, v43, v47
	global_store_dwordx4 v[86:87], v[116:119], off offset:-32
	s_waitcnt vmcnt(4)
	v_cvt_pk_bf16_f32 v120, v48, v52
	v_cvt_pk_bf16_f32 v121, v56, v60
	v_cvt_pk_bf16_f32 v122, v64, v68
	v_cvt_pk_bf16_f32 v123, v72, v76
	global_store_dwordx4 v[88:89], v[120:123], off offset:-32
	v_cvt_pk_bf16_f32 v124, v49, v53
	v_cvt_pk_bf16_f32 v125, v57, v61
	v_cvt_pk_bf16_f32 v126, v65, v69
	v_cvt_pk_bf16_f32 v127, v73, v77
	global_store_dwordx4 v[90:91], v[124:127], off offset:-32
	v_cvt_pk_bf16_f32 v116, v50, v54
	v_cvt_pk_bf16_f32 v117, v58, v62
	v_cvt_pk_bf16_f32 v118, v66, v70
	v_cvt_pk_bf16_f32 v119, v74, v78
	global_store_dwordx4 v[92:93], v[116:119], off offset:-32
	v_cvt_pk_bf16_f32 v120, v51, v55
	v_cvt_pk_bf16_f32 v121, v59, v63
	v_cvt_pk_bf16_f32 v122, v67, v71
	v_cvt_pk_bf16_f32 v123, v75, v79
	global_store_dwordx4 v[94:95], v[120:123], off offset:-32

.LBB0_46:
	s_andn2_b64 vcc, exec, s[4:5]
	s_cbranch_vccnz .LBB0_49
	s_load_dwordx2 s[44:45], s[8:9], 0x88
	s_load_dwordx2 s[78:79], s[8:9], 0xa8
	s_lshr_b32 s4, s48, 6
	s_mov_b32 s5, s13
	s_lshl_b64 s[6:7], s[4:5], 20
	s_or_b64 s[6:7], s[6:7], s[12:13]
	s_lshl_b64 s[4:5], s[4:5], 21
	s_lshl_b32 s12, s17, 6
	s_waitcnt lgkmcnt(0)
	s_add_u32 s6, s44, s6
	s_addc_u32 s7, s45, s7
	v_lshl_add_u64 v[0:1], s[6:7], 0, v[128:129]
	s_add_u32 s6, s78, s43
	s_addc_u32 s7, s79, 0
	v_bitop3_b32 v2, s12, v157, v130 bitop3:0xc8
	s_add_u32 s4, s6, s4
	v_add_lshl_u32 v2, v153, v2, 11
	v_mov_b32_e32 v3, v129
	s_addc_u32 s5, s7, s5
	v_lshl_add_u64 v[2:3], s[4:5], 0, v[2:3]
	v_lshl_add_u64 v[2:3], v[2:3], 0, s[30:31]
	s_mov_b64 s[6:7], 0
	v_lshl_add_u64 v[8:9], v[0:1], 0, s[6:7]
	v_and_b32_e32 v10, 7, v130
	v_lshrrev_b32_e32 v11, 3, v130
	v_readfirstlane_b32 s4, v8
	v_readfirstlane_b32 s5, v9
	v_lshlrev_b32_e32 v10, 15, v10
	v_lshl_add_u32 v10, v11, 4, v10
	v_lshlrev_b32_e32 v12, 4, v11
	v_mov_b32_e32 v11, 0
	v_lshl_add_u64 v[8:9], s[4:5], 0, v[10:11]
	global_load_dwordx4 v[16:19], v[8:9], off nt
	s_mov_b64 s[4:5], 0x1000
	v_lshl_add_u64 v[102:103], v[8:9], 0, s[4:5]
	global_load_dwordx4 v[20:23], v[102:103], off nt
	s_mov_b64 s[4:5], 0x2000
	v_lshl_add_u64 v[104:105], v[8:9], 0, s[4:5]
	global_load_dwordx4 v[24:27], v[104:105], off nt
	s_mov_b64 s[4:5], 0x3000
	v_lshl_add_u64 v[106:107], v[8:9], 0, s[4:5]
	global_load_dwordx4 v[28:31], v[106:107], off nt
	s_mov_b64 s[4:5], 0x4000
	v_lshl_add_u64 v[108:109], v[8:9], 0, s[4:5]
	global_load_dwordx4 v[32:35], v[108:109], off nt
	s_mov_b64 s[4:5], 0x5000
	v_lshl_add_u64 v[110:111], v[8:9], 0, s[4:5]
	global_load_dwordx4 v[36:39], v[110:111], off nt
	s_mov_b64 s[4:5], 0x6000
	v_lshl_add_u64 v[112:113], v[8:9], 0, s[4:5]
	global_load_dwordx4 v[40:43], v[112:113], off nt
	s_mov_b64 s[4:5], 0x7000
	v_lshl_add_u64 v[114:115], v[8:9], 0, s[4:5]
	global_load_dwordx4 v[44:47], v[114:115], off nt
	global_load_dwordx4 v[48:51], v[8:9], off offset:128 nt
	global_load_dwordx4 v[52:55], v[102:103], off offset:128 nt
	global_load_dwordx4 v[56:59], v[104:105], off offset:128 nt
	global_load_dwordx4 v[60:63], v[106:107], off offset:128 nt
	global_load_dwordx4 v[64:67], v[108:109], off offset:128 nt
	global_load_dwordx4 v[68:71], v[110:111], off offset:128 nt
	global_load_dwordx4 v[72:75], v[112:113], off offset:128 nt
	global_load_dwordx4 v[76:79], v[114:115], off offset:128 nt
	ds_bpermute_b32 v80, v12, v2
	ds_bpermute_b32 v81, v12, v3
	v_add_u32_e32 v13, 4, v12
	ds_bpermute_b32 v82, v13, v2
	ds_bpermute_b32 v83, v13, v3
	v_add_u32_e32 v13, 8, v12
	ds_bpermute_b32 v84, v13, v2
	ds_bpermute_b32 v85, v13, v3
	v_add_u32_e32 v13, 12, v12
	ds_bpermute_b32 v86, v13, v2
	ds_bpermute_b32 v87, v13, v3
	v_add_u32_e32 v13, 128, v12
	ds_bpermute_b32 v88, v13, v2
	ds_bpermute_b32 v89, v13, v3
	v_add_u32_e32 v13, 132, v12
	ds_bpermute_b32 v90, v13, v2
	ds_bpermute_b32 v91, v13, v3
	v_add_u32_e32 v13, 136, v12
	ds_bpermute_b32 v92, v13, v2
	ds_bpermute_b32 v93, v13, v3
	v_add_u32_e32 v13, 140, v12
	ds_bpermute_b32 v94, v13, v2
	ds_bpermute_b32 v95, v13, v3
	v_and_b32_e32 v14, 7, v130
	v_lshlrev_b32_e32 v14, 4, v14
	v_mov_b32_e32 v15, 0
	s_waitcnt lgkmcnt(0)
	v_lshl_add_u64 v[80:81], v[80:81], 0, v[14:15]
	v_lshl_add_u64 v[82:83], v[82:83], 0, v[14:15]
	v_lshl_add_u64 v[84:85], v[84:85], 0, v[14:15]
	v_lshl_add_u64 v[86:87], v[86:87], 0, v[14:15]
	v_lshl_add_u64 v[88:89], v[88:89], 0, v[14:15]
	v_lshl_add_u64 v[90:91], v[90:91], 0, v[14:15]
	v_lshl_add_u64 v[92:93], v[92:93], 0, v[14:15]
	v_lshl_add_u64 v[94:95], v[94:95], 0, v[14:15]
	s_waitcnt vmcnt(8)
	v_cvt_pk_bf16_f32 v116, v16, v20
	v_cvt_pk_bf16_f32 v117, v24, v28
	v_cvt_pk_bf16_f32 v118, v32, v36
	v_cvt_pk_bf16_f32 v119, v40, v44
	global_store_dwordx4 v[80:81], v[116:119], off offset:-32
	v_cvt_pk_bf16_f32 v120, v17, v21
	v_cvt_pk_bf16_f32 v121, v25, v29
	v_cvt_pk_bf16_f32 v122, v33, v37
	v_cvt_pk_bf16_f32 v123, v41, v45
	global_store_dwordx4 v[82:83], v[120:123], off offset:-32
	v_cvt_pk_bf16_f32 v124, v18, v22
	v_cvt_pk_bf16_f32 v125, v26, v30
	v_cvt_pk_bf16_f32 v126, v34, v38
	v_cvt_pk_bf16_f32 v127, v42, v46
	global_store_dwordx4 v[84:85], v[124:127], off offset:-32
	v_cvt_pk_bf16_f32 v116, v19, v23
	v_cvt_pk_bf16_f32 v117, v27, v31
	v_cvt_pk_bf16_f32 v118, v35, v39
	v_cvt_pk_bf16_f32 v119, v43, v47
	global_store_dwordx4 v[86:87], v[116:119], off offset:-32
	s_waitcnt vmcnt(4)
	v_cvt_pk_bf16_f32 v120, v48, v52
	v_cvt_pk_bf16_f32 v121, v56, v60
	v_cvt_pk_bf16_f32 v122, v64, v68
	v_cvt_pk_bf16_f32 v123, v72, v76
	global_store_dwordx4 v[88:89], v[120:123], off offset:-32
	v_cvt_pk_bf16_f32 v124, v49, v53
	v_cvt_pk_bf16_f32 v125, v57, v61
	v_cvt_pk_bf16_f32 v126, v65, v69
	v_cvt_pk_bf16_f32 v127, v73, v77
	global_store_dwordx4 v[90:91], v[124:127], off offset:-32
	v_cvt_pk_bf16_f32 v116, v50, v54
	v_cvt_pk_bf16_f32 v117, v58, v62
	v_cvt_pk_bf16_f32 v118, v66, v70
	v_cvt_pk_bf16_f32 v119, v74, v78
	global_store_dwordx4 v[92:93], v[116:119], off offset:-32
	v_cvt_pk_bf16_f32 v120, v51, v55
	v_cvt_pk_bf16_f32 v121, v59, v63
	v_cvt_pk_bf16_f32 v122, v67, v71
	v_cvt_pk_bf16_f32 v123, v75, v79
	global_store_dwordx4 v[94:95], v[120:123], off offset:-32

.LBB0_50:
	s_andn2_b64 vcc, exec, s[4:5]
	s_cbranch_vccnz .LBB0_53
	s_lshl_b64 s[4:5], s[14:15], 14
	s_and_b32 s7, s5, 0x3fff
	s_and_b32 s6, s4, 0xffe00000
	s_load_dwordx2 s[4:5], s[8:9], 0x80
	s_load_dwordx2 s[44:45], s[8:9], 0xa8
	s_and_b32 s12, s42, 7
	s_lshl_b32 s43, s12, 18
	s_lshl_b32 s12, s12, 7
	s_lshl_b32 s78, s17, 6
	s_waitcnt lgkmcnt(0)
	s_add_u32 s4, s4, s43
	s_addc_u32 s5, s5, 0
	v_bitop3_b32 v2, s78, v157, v130 bitop3:0xc8
	v_lshl_add_u64 v[0:1], s[4:5], 0, v[128:129]
	s_add_u32 s4, s44, s12
	v_add_lshl_u32 v2, v153, v2, 11
	v_mov_b32_e32 v3, v129
	s_addc_u32 s5, s45, 0
	v_lshl_add_u64 v[2:3], s[4:5], 0, v[2:3]
	v_lshl_add_u64 v[2:3], v[2:3], 0, s[34:35]
	s_mov_b32 s12, 8
	v_lshl_add_u64 v[8:9], v[0:1], 0, s[6:7]
	v_and_b32_e32 v10, 7, v130
	v_lshrrev_b32_e32 v11, 3, v130
	v_readfirstlane_b32 s4, v8
	v_readfirstlane_b32 s5, v9
	v_lshlrev_b32_e32 v10, 15, v10
	v_lshl_add_u32 v10, v11, 4, v10
	v_lshlrev_b32_e32 v12, 4, v11
	v_mov_b32_e32 v11, 0
	v_lshl_add_u64 v[8:9], s[4:5], 0, v[10:11]
	global_load_dwordx4 v[16:19], v[8:9], off nt
	s_mov_b64 s[4:5], 0x1000
	v_lshl_add_u64 v[102:103], v[8:9], 0, s[4:5]
	global_load_dwordx4 v[20:23], v[102:103], off nt
	s_mov_b64 s[4:5], 0x2000
	v_lshl_add_u64 v[104:105], v[8:9], 0, s[4:5]
	global_load_dwordx4 v[24:27], v[104:105], off nt
	s_mov_b64 s[4:5], 0x3000
	v_lshl_add_u64 v[106:107], v[8:9], 0, s[4:5]
	global_load_dwordx4 v[28:31], v[106:107], off nt
	s_mov_b64 s[4:5], 0x4000
	v_lshl_add_u64 v[108:109], v[8:9], 0, s[4:5]
	global_load_dwordx4 v[32:35], v[108:109], off nt
	s_mov_b64 s[4:5], 0x5000
	v_lshl_add_u64 v[110:111], v[8:9], 0, s[4:5]
	global_load_dwordx4 v[36:39], v[110:111], off nt
	s_mov_b64 s[4:5], 0x6000
	v_lshl_add_u64 v[112:113], v[8:9], 0, s[4:5]
	global_load_dwordx4 v[40:43], v[112:113], off nt
	s_mov_b64 s[4:5], 0x7000
	v_lshl_add_u64 v[114:115], v[8:9], 0, s[4:5]
	global_load_dwordx4 v[44:47], v[114:115], off nt
	global_load_dwordx4 v[48:51], v[8:9], off offset:128 nt
	global_load_dwordx4 v[52:55], v[102:103], off offset:128 nt
	global_load_dwordx4 v[56:59], v[104:105], off offset:128 nt
	global_load_dwordx4 v[60:63], v[106:107], off offset:128 nt
	global_load_dwordx4 v[64:67], v[108:109], off offset:128 nt
	global_load_dwordx4 v[68:71], v[110:111], off offset:128 nt
	global_load_dwordx4 v[72:75], v[112:113], off offset:128 nt
	global_load_dwordx4 v[76:79], v[114:115], off offset:128 nt
	v_lshl_add_u64 v[4:5], v[2:3], 0, s[6:7]
	ds_bpermute_b32 v80, v12, v4
	ds_bpermute_b32 v81, v12, v5
	v_add_u32_e32 v13, 4, v12
	ds_bpermute_b32 v82, v13, v4
	ds_bpermute_b32 v83, v13, v5
	v_add_u32_e32 v13, 8, v12
	ds_bpermute_b32 v84, v13, v4
	ds_bpermute_b32 v85, v13, v5
	v_add_u32_e32 v13, 12, v12
	ds_bpermute_b32 v86, v13, v4
	ds_bpermute_b32 v87, v13, v5
	v_add_u32_e32 v13, 128, v12
	ds_bpermute_b32 v88, v13, v4
	ds_bpermute_b32 v89, v13, v5
	v_add_u32_e32 v13, 132, v12
	ds_bpermute_b32 v90, v13, v4
	ds_bpermute_b32 v91, v13, v5
	v_add_u32_e32 v13, 136, v12
	ds_bpermute_b32 v92, v13, v4
	ds_bpermute_b32 v93, v13, v5
	v_add_u32_e32 v13, 140, v12
	ds_bpermute_b32 v94, v13, v4
	ds_bpermute_b32 v95, v13, v5
	v_and_b32_e32 v14, 7, v130
	v_lshlrev_b32_e32 v14, 4, v14
	v_mov_b32_e32 v15, 0
	s_waitcnt lgkmcnt(0)
	v_lshl_add_u64 v[80:81], v[80:81], 0, v[14:15]
	v_lshl_add_u64 v[82:83], v[82:83], 0, v[14:15]
	v_lshl_add_u64 v[84:85], v[84:85], 0, v[14:15]
	v_lshl_add_u64 v[86:87], v[86:87], 0, v[14:15]
	v_lshl_add_u64 v[88:89], v[88:89], 0, v[14:15]
	v_lshl_add_u64 v[90:91], v[90:91], 0, v[14:15]
	v_lshl_add_u64 v[92:93], v[92:93], 0, v[14:15]
	v_lshl_add_u64 v[94:95], v[94:95], 0, v[14:15]
	s_waitcnt vmcnt(8)
	v_cvt_pk_bf16_f32 v116, v16, v20
	v_cvt_pk_bf16_f32 v117, v24, v28
	v_cvt_pk_bf16_f32 v118, v32, v36
	v_cvt_pk_bf16_f32 v119, v40, v44
	global_store_dwordx4 v[80:81], v[116:119], off offset:-32
	v_cvt_pk_bf16_f32 v120, v17, v21
	v_cvt_pk_bf16_f32 v121, v25, v29
	v_cvt_pk_bf16_f32 v122, v33, v37
	v_cvt_pk_bf16_f32 v123, v41, v45
	global_store_dwordx4 v[82:83], v[120:123], off offset:-32
	v_cvt_pk_bf16_f32 v124, v18, v22
	v_cvt_pk_bf16_f32 v125, v26, v30
	v_cvt_pk_bf16_f32 v126, v34, v38
	v_cvt_pk_bf16_f32 v127, v42, v46
	global_store_dwordx4 v[84:85], v[124:127], off offset:-32
	v_cvt_pk_bf16_f32 v116, v19, v23
	v_cvt_pk_bf16_f32 v117, v27, v31
	v_cvt_pk_bf16_f32 v118, v35, v39
	v_cvt_pk_bf16_f32 v119, v43, v47
	global_store_dwordx4 v[86:87], v[116:119], off offset:-32
	s_waitcnt vmcnt(4)
	v_cvt_pk_bf16_f32 v120, v48, v52
	v_cvt_pk_bf16_f32 v121, v56, v60
	v_cvt_pk_bf16_f32 v122, v64, v68
	v_cvt_pk_bf16_f32 v123, v72, v76
	global_store_dwordx4 v[88:89], v[120:123], off offset:-32
	v_cvt_pk_bf16_f32 v124, v49, v53
	v_cvt_pk_bf16_f32 v125, v57, v61
	v_cvt_pk_bf16_f32 v126, v65, v69
	v_cvt_pk_bf16_f32 v127, v73, v77
	global_store_dwordx4 v[90:91], v[124:127], off offset:-32
	v_cvt_pk_bf16_f32 v116, v50, v54
	v_cvt_pk_bf16_f32 v117, v58, v62
	v_cvt_pk_bf16_f32 v118, v66, v70
	v_cvt_pk_bf16_f32 v119, v74, v78
	global_store_dwordx4 v[92:93], v[116:119], off offset:-32
	v_cvt_pk_bf16_f32 v120, v51, v55
	v_cvt_pk_bf16_f32 v121, v59, v63
	v_cvt_pk_bf16_f32 v122, v67, v71
	v_cvt_pk_bf16_f32 v123, v75, v79
	global_store_dwordx4 v[94:95], v[120:123], off offset:-32

.LBB0_54:
	s_andn2_b64 vcc, exec, s[4:5]
	s_cbranch_vccnz .LBB0_57
	s_lshr_b32 s12, s49, 8
	s_and_b32 s44, s42, 15
	s_load_dwordx2 s[42:43], s[8:9], 0x98
	s_lshl_b64 s[4:5], s[12:13], 22
	s_lshl_b32 s6, s44, 18
	s_or_b32 s4, s4, s6
	s_lshl_b64 s[6:7], s[12:13], 21
	s_lshl_b32 s12, s44, 7
	s_load_dwordx2 s[44:45], s[8:9], 0xa8
	s_lshl_b32 s78, s17, 6
	s_waitcnt lgkmcnt(0)
	s_add_u32 s4, s42, s4
	s_addc_u32 s5, s43, s5
	v_lshl_add_u64 v[0:1], s[4:5], 0, v[128:129]
	s_add_u32 s4, s44, s12
	s_addc_u32 s5, s45, 0
	v_bitop3_b32 v2, s78, v157, v130 bitop3:0xc8
	s_add_u32 s4, s4, s6
	v_add_lshl_u32 v128, v153, v2, 11
	s_addc_u32 s5, s5, s7
	v_lshl_add_u64 v[2:3], s[4:5], 0, v[128:129]
	v_lshl_add_u64 v[2:3], v[2:3], 0, s[36:37]
	s_mov_b64 s[6:7], 0
	v_lshl_add_u64 v[8:9], v[0:1], 0, s[6:7]
	v_and_b32_e32 v10, 7, v130
	v_lshrrev_b32_e32 v11, 3, v130
	v_readfirstlane_b32 s4, v8
	v_readfirstlane_b32 s5, v9
	v_lshlrev_b32_e32 v10, 15, v10
	v_lshl_add_u32 v10, v11, 4, v10
	v_lshlrev_b32_e32 v12, 4, v11
	v_mov_b32_e32 v11, 0
	v_lshl_add_u64 v[8:9], s[4:5], 0, v[10:11]
	global_load_dwordx4 v[16:19], v[8:9], off nt
	s_mov_b64 s[4:5], 0x1000
	v_lshl_add_u64 v[102:103], v[8:9], 0, s[4:5]
	global_load_dwordx4 v[20:23], v[102:103], off nt
	s_mov_b64 s[4:5], 0x2000
	v_lshl_add_u64 v[104:105], v[8:9], 0, s[4:5]
	global_load_dwordx4 v[24:27], v[104:105], off nt
	s_mov_b64 s[4:5], 0x3000
	v_lshl_add_u64 v[106:107], v[8:9], 0, s[4:5]
	global_load_dwordx4 v[28:31], v[106:107], off nt
	s_mov_b64 s[4:5], 0x4000
	v_lshl_add_u64 v[108:109], v[8:9], 0, s[4:5]
	global_load_dwordx4 v[32:35], v[108:109], off nt
	s_mov_b64 s[4:5], 0x5000
	v_lshl_add_u64 v[110:111], v[8:9], 0, s[4:5]
	global_load_dwordx4 v[36:39], v[110:111], off nt
	s_mov_b64 s[4:5], 0x6000
	v_lshl_add_u64 v[112:113], v[8:9], 0, s[4:5]
	global_load_dwordx4 v[40:43], v[112:113], off nt
	s_mov_b64 s[4:5], 0x7000
	v_lshl_add_u64 v[114:115], v[8:9], 0, s[4:5]
	global_load_dwordx4 v[44:47], v[114:115], off nt
	global_load_dwordx4 v[48:51], v[8:9], off offset:128 nt
	global_load_dwordx4 v[52:55], v[102:103], off offset:128 nt
	global_load_dwordx4 v[56:59], v[104:105], off offset:128 nt
	global_load_dwordx4 v[60:63], v[106:107], off offset:128 nt
	global_load_dwordx4 v[64:67], v[108:109], off offset:128 nt
	global_load_dwordx4 v[68:71], v[110:111], off offset:128 nt
	global_load_dwordx4 v[72:75], v[112:113], off offset:128 nt
	global_load_dwordx4 v[76:79], v[114:115], off offset:128 nt
	ds_bpermute_b32 v80, v12, v2
	ds_bpermute_b32 v81, v12, v3
	v_add_u32_e32 v13, 4, v12
	ds_bpermute_b32 v82, v13, v2
	ds_bpermute_b32 v83, v13, v3
	v_add_u32_e32 v13, 8, v12
	ds_bpermute_b32 v84, v13, v2
	ds_bpermute_b32 v85, v13, v3
	v_add_u32_e32 v13, 12, v12
	ds_bpermute_b32 v86, v13, v2
	ds_bpermute_b32 v87, v13, v3
	v_add_u32_e32 v13, 128, v12
	ds_bpermute_b32 v88, v13, v2
	ds_bpermute_b32 v89, v13, v3
	v_add_u32_e32 v13, 132, v12
	ds_bpermute_b32 v90, v13, v2
	ds_bpermute_b32 v91, v13, v3
	v_add_u32_e32 v13, 136, v12
	ds_bpermute_b32 v92, v13, v2
	ds_bpermute_b32 v93, v13, v3
	v_add_u32_e32 v13, 140, v12
	ds_bpermute_b32 v94, v13, v2
	ds_bpermute_b32 v95, v13, v3
	v_and_b32_e32 v14, 7, v130
	v_lshlrev_b32_e32 v14, 4, v14
	v_mov_b32_e32 v15, 0
	s_waitcnt lgkmcnt(0)
	v_lshl_add_u64 v[80:81], v[80:81], 0, v[14:15]
	v_lshl_add_u64 v[82:83], v[82:83], 0, v[14:15]
	v_lshl_add_u64 v[84:85], v[84:85], 0, v[14:15]
	v_lshl_add_u64 v[86:87], v[86:87], 0, v[14:15]
	v_lshl_add_u64 v[88:89], v[88:89], 0, v[14:15]
	v_lshl_add_u64 v[90:91], v[90:91], 0, v[14:15]
	v_lshl_add_u64 v[92:93], v[92:93], 0, v[14:15]
	v_lshl_add_u64 v[94:95], v[94:95], 0, v[14:15]
	s_waitcnt vmcnt(8)
	v_cvt_pk_bf16_f32 v116, v16, v20
	v_cvt_pk_bf16_f32 v117, v24, v28
	v_cvt_pk_bf16_f32 v118, v32, v36
	v_cvt_pk_bf16_f32 v119, v40, v44
	global_store_dwordx4 v[80:81], v[116:119], off offset:-32
	v_cvt_pk_bf16_f32 v120, v17, v21
	v_cvt_pk_bf16_f32 v121, v25, v29
	v_cvt_pk_bf16_f32 v122, v33, v37
	v_cvt_pk_bf16_f32 v123, v41, v45
	global_store_dwordx4 v[82:83], v[120:123], off offset:-32
	v_cvt_pk_bf16_f32 v124, v18, v22
	v_cvt_pk_bf16_f32 v125, v26, v30
	v_cvt_pk_bf16_f32 v126, v34, v38
	v_cvt_pk_bf16_f32 v127, v42, v46
	global_store_dwordx4 v[84:85], v[124:127], off offset:-32
	v_cvt_pk_bf16_f32 v116, v19, v23
	v_cvt_pk_bf16_f32 v117, v27, v31
	v_cvt_pk_bf16_f32 v118, v35, v39
	v_cvt_pk_bf16_f32 v119, v43, v47
	global_store_dwordx4 v[86:87], v[116:119], off offset:-32
	s_waitcnt vmcnt(4)
	v_cvt_pk_bf16_f32 v120, v48, v52
	v_cvt_pk_bf16_f32 v121, v56, v60
	v_cvt_pk_bf16_f32 v122, v64, v68
	v_cvt_pk_bf16_f32 v123, v72, v76
	global_store_dwordx4 v[88:89], v[120:123], off offset:-32
	v_cvt_pk_bf16_f32 v124, v49, v53
	v_cvt_pk_bf16_f32 v125, v57, v61
	v_cvt_pk_bf16_f32 v126, v65, v69
	v_cvt_pk_bf16_f32 v127, v73, v77
	global_store_dwordx4 v[90:91], v[124:127], off offset:-32
	v_cvt_pk_bf16_f32 v116, v50, v54
	v_cvt_pk_bf16_f32 v117, v58, v62
	v_cvt_pk_bf16_f32 v118, v66, v70
	v_cvt_pk_bf16_f32 v119, v74, v78
	global_store_dwordx4 v[92:93], v[116:119], off offset:-32
	v_cvt_pk_bf16_f32 v120, v51, v55
	v_cvt_pk_bf16_f32 v121, v59, v63
	v_cvt_pk_bf16_f32 v122, v67, v71
	v_cvt_pk_bf16_f32 v123, v75, v79
	global_store_dwordx4 v[94:95], v[120:123], off offset:-32

.LBB0_70:
	s_load_dwordx2 s[4:5], s[8:9], 0x48
	s_load_dwordx2 s[44:45], s[8:9], 0xa8
	s_cmpk_gt_u32 s43, 0x5ff
	s_cselect_b32 s43, 0x1800000, 0
	s_cselect_b32 s78, 0xc80000, 0
	s_waitcnt lgkmcnt(0)
	s_add_u32 s4, s4, s43
	s_addc_u32 s5, s5, 0
	s_mul_i32 s42, s42, 0x180000
	s_add_u32 s4, s4, s42
	s_addc_u32 s5, s5, 0
	v_lshlrev_b32_e32 v128, 2, v0
	v_lshlrev_b32_e32 v2, 2, v1
	v_lshrrev_b32_e32 v3, 1, v1
	v_and_b32_e32 v4, 0x7fffffe3, v1
	v_lshl_add_u64 v[0:1], s[4:5], 0, v[128:129]
	s_mul_hi_u32 s4, s12, 0x2aaaaab
	s_lshl_b32 s4, s4, 7
	s_add_u32 s4, s44, s4
	v_and_b32_e32 v2, 16, v2
	v_and_b32_e32 v3, 12, v3
	s_addc_u32 s5, s45, 0
	v_or3_b32 v128, v4, v2, v3
	s_add_u32 s4, s4, s78
	v_lshlrev_b64 v[2:3], 11, v[128:129]
	s_addc_u32 s5, s5, 0
	v_lshl_add_u64 v[2:3], s[4:5], 0, v[2:3]
	v_lshl_add_u64 v[2:3], v[2:3], 0, s[38:39]
	s_mov_b64 s[42:43], 0
	v_mov_b32_e32 v8, v0
	v_mov_b32_e32 v9, v1
	v_and_b32_e32 v10, 7, v130
	v_lshrrev_b32_e32 v11, 3, v130
	v_readfirstlane_b32 s4, v8
	v_readfirstlane_b32 s5, v9
	v_mul_u32_u24_e32 v10, 0x30000, v10
	v_lshl_add_u32 v10, v11, 4, v10
	v_lshlrev_b32_e32 v12, 4, v11
	v_mov_b32_e32 v11, 0
	v_lshl_add_u64 v[8:9], s[4:5], 0, v[10:11]
	global_load_dwordx4 v[16:19], v[8:9], off nt
	s_mov_b64 s[4:5], 0x6000
	v_lshl_add_u64 v[102:103], v[8:9], 0, s[4:5]
	global_load_dwordx4 v[20:23], v[102:103], off nt
	s_mov_b64 s[4:5], 0xc000
	v_lshl_add_u64 v[104:105], v[8:9], 0, s[4:5]
	global_load_dwordx4 v[24:27], v[104:105], off nt
	s_mov_b64 s[4:5], 0x12000
	v_lshl_add_u64 v[106:107], v[8:9], 0, s[4:5]
	global_load_dwordx4 v[28:31], v[106:107], off nt
	s_mov_b64 s[4:5], 0x18000
	v_lshl_add_u64 v[108:109], v[8:9], 0, s[4:5]
	global_load_dwordx4 v[32:35], v[108:109], off nt
	s_mov_b64 s[4:5], 0x1e000
	v_lshl_add_u64 v[110:111], v[8:9], 0, s[4:5]
	global_load_dwordx4 v[36:39], v[110:111], off nt
	s_mov_b64 s[4:5], 0x24000
	v_lshl_add_u64 v[112:113], v[8:9], 0, s[4:5]
	global_load_dwordx4 v[40:43], v[112:113], off nt
	s_mov_b64 s[4:5], 0x2a000
	v_lshl_add_u64 v[114:115], v[8:9], 0, s[4:5]
	global_load_dwordx4 v[44:47], v[114:115], off nt
	global_load_dwordx4 v[48:51], v[8:9], off offset:128 nt
	global_load_dwordx4 v[52:55], v[102:103], off offset:128 nt
	global_load_dwordx4 v[56:59], v[104:105], off offset:128 nt
	global_load_dwordx4 v[60:63], v[106:107], off offset:128 nt
	global_load_dwordx4 v[64:67], v[108:109], off offset:128 nt
	global_load_dwordx4 v[68:71], v[110:111], off offset:128 nt
	global_load_dwordx4 v[72:75], v[112:113], off offset:128 nt
	global_load_dwordx4 v[76:79], v[114:115], off offset:128 nt
	ds_bpermute_b32 v80, v12, v2
	ds_bpermute_b32 v81, v12, v3
	v_add_u32_e32 v13, 4, v12
	ds_bpermute_b32 v82, v13, v2
	ds_bpermute_b32 v83, v13, v3
	v_add_u32_e32 v13, 8, v12
	ds_bpermute_b32 v84, v13, v2
	ds_bpermute_b32 v85, v13, v3
	v_add_u32_e32 v13, 12, v12
	ds_bpermute_b32 v86, v13, v2
	ds_bpermute_b32 v87, v13, v3
	v_add_u32_e32 v13, 128, v12
	ds_bpermute_b32 v88, v13, v2
	ds_bpermute_b32 v89, v13, v3
	v_add_u32_e32 v13, 132, v12
	ds_bpermute_b32 v90, v13, v2
	ds_bpermute_b32 v91, v13, v3
	v_add_u32_e32 v13, 136, v12
	ds_bpermute_b32 v92, v13, v2
	ds_bpermute_b32 v93, v13, v3
	v_add_u32_e32 v13, 140, v12
	ds_bpermute_b32 v94, v13, v2
	ds_bpermute_b32 v95, v13, v3
	v_and_b32_e32 v14, 7, v130
	v_lshlrev_b32_e32 v14, 4, v14
	v_mov_b32_e32 v15, 0
	s_waitcnt lgkmcnt(0)
	v_lshl_add_u64 v[80:81], v[80:81], 0, v[14:15]
	v_lshl_add_u64 v[82:83], v[82:83], 0, v[14:15]
	v_lshl_add_u64 v[84:85], v[84:85], 0, v[14:15]
	v_lshl_add_u64 v[86:87], v[86:87], 0, v[14:15]
	v_lshl_add_u64 v[88:89], v[88:89], 0, v[14:15]
	v_lshl_add_u64 v[90:91], v[90:91], 0, v[14:15]
	v_lshl_add_u64 v[92:93], v[92:93], 0, v[14:15]
	v_lshl_add_u64 v[94:95], v[94:95], 0, v[14:15]
	s_waitcnt vmcnt(8)
	v_cvt_pk_bf16_f32 v116, v16, v20
	v_cvt_pk_bf16_f32 v117, v24, v28
	v_cvt_pk_bf16_f32 v118, v32, v36
	v_cvt_pk_bf16_f32 v119, v40, v44
	global_store_dwordx4 v[80:81], v[116:119], off offset:-32
	v_cvt_pk_bf16_f32 v120, v17, v21
	v_cvt_pk_bf16_f32 v121, v25, v29
	v_cvt_pk_bf16_f32 v122, v33, v37
	v_cvt_pk_bf16_f32 v123, v41, v45
	global_store_dwordx4 v[82:83], v[120:123], off offset:-32
	v_cvt_pk_bf16_f32 v124, v18, v22
	v_cvt_pk_bf16_f32 v125, v26, v30
	v_cvt_pk_bf16_f32 v126, v34, v38
	v_cvt_pk_bf16_f32 v127, v42, v46
	global_store_dwordx4 v[84:85], v[124:127], off offset:-32
	v_cvt_pk_bf16_f32 v116, v19, v23
	v_cvt_pk_bf16_f32 v117, v27, v31
	v_cvt_pk_bf16_f32 v118, v35, v39
	v_cvt_pk_bf16_f32 v119, v43, v47
	global_store_dwordx4 v[86:87], v[116:119], off offset:-32
	s_waitcnt vmcnt(4)
	v_cvt_pk_bf16_f32 v120, v48, v52
	v_cvt_pk_bf16_f32 v121, v56, v60
	v_cvt_pk_bf16_f32 v122, v64, v68
	v_cvt_pk_bf16_f32 v123, v72, v76
	global_store_dwordx4 v[88:89], v[120:123], off offset:-32
	v_cvt_pk_bf16_f32 v124, v49, v53
	v_cvt_pk_bf16_f32 v125, v57, v61
	v_cvt_pk_bf16_f32 v126, v65, v69
	v_cvt_pk_bf16_f32 v127, v73, v77
	global_store_dwordx4 v[90:91], v[124:127], off offset:-32
	v_cvt_pk_bf16_f32 v116, v50, v54
	v_cvt_pk_bf16_f32 v117, v58, v62
	v_cvt_pk_bf16_f32 v118, v66, v70
	v_cvt_pk_bf16_f32 v119, v74, v78
	global_store_dwordx4 v[92:93], v[116:119], off offset:-32
	v_cvt_pk_bf16_f32 v120, v51, v55
	v_cvt_pk_bf16_f32 v121, v59, v63
	v_cvt_pk_bf16_f32 v122, v67, v71
	v_cvt_pk_bf16_f32 v123, v75, v79
	global_store_dwordx4 v[94:95], v[120:123], off offset:-32
